# gather: the full vmcnt wait at the top of each token (which only waited for the previous token's output stores) removed; one full wait in the preheader instead
# speedup vs baseline: 1.0068x; 1.0016x over previous
; DEV int opaque_tid() { int t = (int)threadIdx.x; asm volatile("" : "+v"(t)); return t; }
; __device__ void peer_gather_phase(const Params& P, int l, bool do_store) {
;   const int lane = opaque_tid() & 63, w = opaque_tid() >> 6;
;   const unsigned char* U = P.U8 + (size_t)l * 16384 * 768 + (lane & 31) * 24;
;   const unsigned char* V = P.V8 + (size_t)l * 16384 * 512 + lane * 8;
;   const float* SU = P.SU + l * 16384;
;   const float* SV = P.SV + l * 16384;
;   int nev0, nev1; float ngv0, ngv1; uint4 nxa, nxc;
;   {
;     const int t = blockIdx.x * 4 + w;
;     nev0 = P.EXP[(size_t)t * 128 + lane]; nev1 = P.EXP[(size_t)t * 128 + 64 + lane];
;     ngv0 = P.GATE[(size_t)t * 128 + lane]; ngv1 = P.GATE[(size_t)t * 128 + 64 + lane];
;     const bf16_t* xb = P.XB + (size_t)t * 1024 + lane * 16;
;     nxa = *(const uint4*)xb; nxc = *(const uint4*)(xb + 8);
;   }
; __device__ void run_phase(const Params& P, int ph, char* smem, bool do_store) {
;   if (ph == 0) { phase_prologue(P); return; }
;   const int l = (ph - 1) >> 3, sub = (ph - 1) & 7;
;   const int G = gridDim.x, bid = blockIdx.x;
;   switch (sub) {
.LBB0_14:
	v_readlane_b32 s4, v248, 27
	s_add_i32 s4, s4, 1
	v_readlane_b32 s2, v249, 37
	s_cmp_eq_u32 s4, s2
	v_writelane_b32 v248, s4, 27
	s_cselect_b64 s[4:5], -1, 0
	v_writelane_b32 v248, s4, 32
	s_mov_b64 s[0:1], -1
	s_nop 0
	v_writelane_b32 v248, s5, 33
	v_readlane_b32 s4, v249, 38
	v_readlane_b32 s5, v249, 39
	s_and_b64 vcc, exec, s[4:5]
	s_cbranch_vccz .LBB0_310
	v_readlane_b32 s0, v251, 58
	v_readlane_b32 s1, v251, 59
	s_load_dword s0, s[0:1], 0x0
	s_waitcnt lgkmcnt(0)
	v_writelane_b32 v248, s0, 34
	s_nop 1
	v_writelane_b32 v248, s1, 35
	v_readlane_b32 s0, v249, 40
	s_cmp_lt_i32 s0, 4
	s_mov_b64 s[0:1], -1
	s_cbranch_scc1 .LBB0_65
	v_readlane_b32 s0, v249, 40
	s_cmp_lt_i32 s0, 6
	s_mov_b64 s[0:1], -1
	s_cbranch_scc1 .LBB0_39
	v_readlane_b32 s0, v249, 40
	s_cmp_gt_i32 s0, 6
	s_cbranch_scc0 .LBB0_38
	v_readlane_b32 s0, v251, 60
	v_readlane_b32 s1, v251, 61
	v_mov_b32_e32 v0, v202
	v_mov_b32_e32 v1, v202
	s_andn2_b64 vcc, exec, s[0:1]
	s_cbranch_vccnz .LBB0_38
	v_ashrrev_i32_e32 v73, 6, v1
	v_and_b32_e32 v1, 31, v0
	v_readlane_b32 s0, v249, 41
	v_mul_u32_u24_e32 v176, 24, v1
	v_readlane_b32 s1, v249, 42
	v_and_b32_e32 v72, 63, v0
	v_readlane_b32 s4, v251, 2
	v_lshl_add_u64 v[74:75], s[0:1], 0, v[176:177]
	v_readlane_b32 s0, v249, 43
	v_lshlrev_b32_e32 v176, 3, v72
	v_readlane_b32 s1, v249, 44
	v_readlane_b32 s5, v251, 3
	v_readlane_b32 s6, v251, 4
	v_lshl_add_u64 v[76:77], s[0:1], 0, v[176:177]
	v_readlane_b32 s0, v251, 62
	v_lshlrev_b32_e32 v176, 5, v72
	v_readlane_b32 s7, v251, 5
	v_add_u32_e32 v2, s0, v73
	v_ashrrev_i32_e32 v3, 31, v2
	v_lshlrev_b64 v[4:5], 11, v[2:3]
	v_lshl_add_u64 v[4:5], s[28:29], 0, v[4:5]
	v_lshlrev_b64 v[2:3], 9, v[2:3]
	v_lshl_add_u64 v[4:5], v[4:5], 0, v[176:177]
	v_lshl_or_b32 v2, v72, 2, v2
	global_load_dwordx4 v[64:67], v[4:5], off offset:16
	global_load_dwordx4 v[68:71], v[4:5], off
	v_lshl_add_u64 v[4:5], s[4:5], 0, v[2:3]
	v_lshl_add_u64 v[2:3], s[6:7], 0, v[2:3]
	global_load_dword v93, v[4:5], off offset:256
	global_load_dword v91, v[4:5], off
	global_load_dword v188, v[2:3], off offset:256
	global_load_dword v179, v[2:3], off
	v_readlane_b32 s0, v249, 49
	v_readlane_b32 s4, v248, 32
	v_readlane_b32 s1, v249, 50
	v_readlane_b32 s5, v248, 33
	s_and_b64 s[38:39], s[0:1], s[4:5]
	v_readlane_b32 s0, v248, 1
	v_readlane_b32 s1, v248, 2
	s_and_b64 s[0:1], s[0:1], s[4:5]
	s_xor_b64 s[0:1], s[0:1], -1
	v_writelane_b32 v248, s0, 45
	v_lshl_add_u64 v[78:79], s[28:29], 0, v[176:177]
	v_lshlrev_b32_e32 v176, 6, v72
	v_writelane_b32 v248, s1, 46
	v_readlane_b32 s0, v249, 54
	v_readlane_b32 s1, v249, 55
	v_lshlrev_b32_e32 v0, 5, v0
	v_readlane_b32 s44, v252, 12
	v_lshl_add_u64 v[82:83], s[0:1], 0, v[176:177]
	v_readlane_b32 s0, v249, 56
	v_readlane_b32 s1, v249, 57
	v_lshlrev_b32_e32 v2, 4, v72
	v_and_b32_e32 v0, 0x3e0, v0
	v_readlane_b32 s58, v252, 26
	v_readlane_b32 s59, v252, 27
	v_lshl_add_u64 v[84:85], s[0:1], 0, v[176:177]
	v_readlane_b32 s0, v249, 5
	v_cmp_lt_u32_e64 s[40:41], 31, v72
	v_lshl_add_u64 v[80:81], s[58:59], 0, v[176:177]
	v_lshlrev_b32_e32 v86, 1, v0
	v_lshlrev_b32_e32 v176, 1, v2
	v_mov_b32_e32 v87, v177
	s_mov_b32 s2, s0
	s_movk_i32 s33, 0x300
	v_readlane_b32 s45, v252, 13
	v_readlane_b32 s46, v252, 14
	v_readlane_b32 s47, v252, 15
	v_readlane_b32 s48, v252, 16
	v_readlane_b32 s49, v252, 17
	v_readlane_b32 s50, v252, 18
	v_readlane_b32 s51, v252, 19
	v_readlane_b32 s52, v252, 20
	v_readlane_b32 s53, v252, 21
	v_readlane_b32 s54, v252, 22
	v_readlane_b32 s55, v252, 23
	v_readlane_b32 s56, v252, 24
	v_readlane_b32 s57, v252, 25
	v_readlane_b32 s1, v249, 6
	v_lshrrev_b32_e32 v74, 5, v72
	v_lshlrev_b32_e32 v74, 2, v74
	v_lshl_add_u32 v74, v73, 9, v74
	v_lshlrev_b32_e32 v75, 2, v72
	v_lshl_add_u32 v75, v73, 9, v75
	s_waitcnt vmcnt(0)
	s_branch .LBB0_21

; __device__ void peer_gather_phase(const Params& P, int l, bool do_store) {
;     ...
;   for (int r4 = blockIdx.x; r4 < T_TOK / 4; r4 += gridDim.x) {
;     const int t = r4 * 4 + w;
;     f32x2 xf[8];
;     const int ev0 = nev0, ev1 = nev1; const float gv0 = ngv0, gv1 = ngv1;
;     {
;       const uint4 xa = nxa, xc = nxc;
;       xf[0] = f32x2{lo_f(xa.x), hi_f(xa.x)}; xf[1] = f32x2{lo_f(xa.y), hi_f(xa.y)}; xf[2] = f32x2{lo_f(xa.z), hi_f(xa.z)}; xf[3] = f32x2{lo_f(xa.w), hi_f(xa.w)};
;       xf[4] = f32x2{lo_f(xc.x), hi_f(xc.x)}; xf[5] = f32x2{lo_f(xc.y), hi_f(xc.y)}; xf[6] = f32x2{lo_f(xc.z), hi_f(xc.z)}; xf[7] = f32x2{lo_f(xc.w), hi_f(xc.w)};
;     }
;     f32x2 xu[16];
;     {
;       const bf16_t* xq = P.XB + (size_t)t * 1024 + (lane & 31) * 32;
;       const uint4 q0 = *(const uint4*)xq, q1 = *(const uint4*)(xq + 8), q2 = *(const uint4*)(xq + 16), q3 = *(const uint4*)(xq + 24);
;       xu[0] = f32x2{lo_f(q0.x), hi_f(q0.x)}; xu[1] = f32x2{lo_f(q0.y), hi_f(q0.y)}; xu[2] = f32x2{lo_f(q0.z), hi_f(q0.z)}; xu[3] = f32x2{lo_f(q0.w), hi_f(q0.w)};
;       xu[4] = f32x2{lo_f(q1.x), hi_f(q1.x)}; xu[5] = f32x2{lo_f(q1.y), hi_f(q1.y)}; xu[6] = f32x2{lo_f(q1.z), hi_f(q1.z)}; xu[7] = f32x2{lo_f(q1.w), hi_f(q1.w)};
;       xu[8] = f32x2{lo_f(q2.x), hi_f(q2.x)}; xu[9] = f32x2{lo_f(q2.y), hi_f(q2.y)}; xu[10] = f32x2{lo_f(q2.z), hi_f(q2.z)}; xu[11] = f32x2{lo_f(q2.w), hi_f(q2.w)};
;       xu[12] = f32x2{lo_f(q3.x), hi_f(q3.x)}; xu[13] = f32x2{lo_f(q3.y), hi_f(q3.y)}; xu[14] = f32x2{lo_f(q3.z), hi_f(q3.z)}; xu[15] = f32x2{lo_f(q3.w), hi_f(q3.w)};
;     }
;     f32x2 y[8];
; #pragma unroll
;     for (int k = 0; k < 8; ++k) y[k] = f32x2{0.f, 0.f};
;     {
;       const int r4n = (r4 + (int)gridDim.x < T_TOK / 4) ? r4 + (int)gridDim.x : r4;
;       const int tn = r4n * 4 + w;
;       nev0 = P.EXP[(size_t)tn * 128 + lane]; nev1 = P.EXP[(size_t)tn * 128 + 64 + lane];
;       ngv0 = P.GATE[(size_t)tn * 128 + lane]; ngv1 = P.GATE[(size_t)tn * 128 + 64 + lane];
;       const bf16_t* xbn = P.XB + (size_t)tn * 1024 + lane * 16;
;       nxa = *(const uint4*)xbn; nxc = *(const uint4*)(xbn + 8);
;     }
;     const float sux0 = SU[ev0], sux1 = SU[ev1];
;     const float gsx0 = gv0 * SV[ev0], gsx1 = gv1 * SV[ev1];
;     const bool uphi = (lane >= 32);
;     uint2 uA[12], uB[12]; uint2 vA[8], vB[8];
;     auto load_batch = [&](uint2 (&u6)[12], uint2 (&v8)[8], int bt) {
.LBB0_21:
	v_readlane_b32 s4, v248, 34
	s_mov_b32 s0, s2
	s_add_i32 s2, s2, s4
	s_cmpk_gt_i32 s2, 0x1fff
	s_cselect_b64 s[44:45], -1, 0
	s_cmpk_lt_i32 s2, 0x2000
	v_lshl_add_u32 v16, s0, 2, v73
	s_cselect_b32 s0, s2, s0
	v_lshl_add_u32 v18, s0, 2, v73
	v_ashrrev_i32_e32 v17, 31, v16
	v_readlane_b32 s5, v248, 35
	v_ashrrev_i32_e32 v19, 31, v18
	v_lshlrev_b64 v[0:1], 11, v[16:17]
	v_lshlrev_b64 v[20:21], 9, v[18:19]
	v_readlane_b32 s4, v251, 2
	v_mov_b32_e32 v90, v188
	v_mov_b32_e32 v92, v179
	v_lshl_add_u64 v[88:89], s[28:29], 0, v[0:1]
	v_lshl_or_b32 v20, v72, 2, v20
	v_readlane_b32 s6, v251, 4
	v_readlane_b32 s7, v251, 5
	v_lshlrev_b64 v[18:19], 11, v[18:19]
	v_mov_b32_e32 v28, v93
	v_mov_b32_e32 v29, v91
	v_lshl_add_u64 v[12:13], v[88:89], 0, v[86:87]
	v_lshl_add_u64 v[22:23], s[6:7], 0, v[20:21]
	v_lshl_add_u64 v[18:19], v[78:79], 0, v[18:19]
	v_ashrrev_i32_e32 v93, 31, v92
	v_readlane_b32 s0, v249, 45
	v_ashrrev_i32_e32 v91, 31, v90
	global_load_dwordx4 v[0:3], v[12:13], off offset:48
	global_load_dwordx4 v[4:7], v[12:13], off offset:32
	global_load_dwordx4 v[8:11], v[12:13], off offset:16
	s_nop 0
	global_load_dwordx4 v[12:15], v[12:13], off
	s_nop 0
	global_load_dword v179, v[22:23], off
	global_load_dword v188, v[22:23], off offset:256
	global_load_dwordx4 v[56:59], v[18:19], off offset:16
	global_load_dwordx4 v[60:63], v[18:19], off
	v_lshlrev_b64 v[18:19], 2, v[92:93]
	v_readlane_b32 s1, v249, 46
	v_lshlrev_b64 v[24:25], 2, v[90:91]
	s_nop 0
	v_lshl_add_u64 v[22:23], s[0:1], 0, v[18:19]
	v_lshl_add_u64 v[26:27], s[0:1], 0, v[24:25]
	v_readlane_b32 s0, v249, 47
	v_readlane_b32 s1, v249, 48
	global_load_dword v189, v[22:23], off
	global_load_dword v190, v[26:27], off
	v_lshl_add_u64 v[18:19], s[0:1], 0, v[18:19]
	v_lshl_add_u64 v[22:23], s[0:1], 0, v[24:25]
	global_load_dword v24, v[18:19], off
	s_nop 0
	global_load_dword v22, v[22:23], off
	v_readlane_b32 s5, v251, 3
	v_mov_b32_e32 v130, 0
	s_nop 0
	v_lshl_add_u64 v[20:21], s[4:5], 0, v[20:21]
	v_readlane_b32 s62, v249, 41
	v_readlane_b32 s63, v249, 42
	v_readlane_b32 s64, v249, 43
	v_readlane_b32 s65, v249, 44
	v_and_b32_e32 v195, 31, v72
	v_mul_u32_u24_e32 v195, 24, v195
	v_lshlrev_b32_e32 v227, 3, v72
	v_readlane_b32 s46, v92, 0
	v_readlane_b32 s47, v92, 1
	v_readlane_b32 s48, v92, 2
	v_readlane_b32 s49, v92, 3
	v_readlane_b32 s50, v92, 4
	v_readlane_b32 s51, v92, 5
	v_readlane_b32 s52, v92, 6
	v_readlane_b32 s53, v92, 7
	v_readlane_b32 s54, v92, 8
	v_readlane_b32 s55, v92, 9
	v_readlane_b32 s56, v92, 10
	v_readlane_b32 s57, v92, 11
	v_readlane_b32 s58, v92, 12
	v_readlane_b32 s59, v92, 13
	v_readlane_b32 s60, v92, 14
	v_readlane_b32 s61, v92, 15
	s_mul_i32 s0, s46, 0x300
	s_mul_i32 s1, s47, 0x300
	v_add_u32_e32 v167, s0, v195
	s_and_saveexec_b64 s[98:99], s[40:41]
	v_add_u32_e32 v167, s1, v195
	s_mov_b64 exec, s[98:99]
	global_load_dwordx2 v[54:55], v167, s[62:63] offset:16
	global_load_dwordx4 v[50:53], v167, s[62:63]
	s_mul_i32 s0, s48, 0x300
	s_mul_i32 s1, s49, 0x300
	v_add_u32_e32 v167, s0, v195
	s_and_saveexec_b64 s[98:99], s[40:41]
	v_add_u32_e32 v167, s1, v195
	s_mov_b64 exec, s[98:99]
	global_load_dwordx2 v[48:49], v167, s[62:63] offset:16
	global_load_dwordx4 v[44:47], v167, s[62:63]
	s_mul_i32 s0, s50, 0x300
	s_mul_i32 s1, s51, 0x300
	v_add_u32_e32 v167, s0, v195
	s_and_saveexec_b64 s[98:99], s[40:41]
	v_add_u32_e32 v167, s1, v195
	s_mov_b64 exec, s[98:99]
	global_load_dwordx2 v[42:43], v167, s[62:63] offset:16
	global_load_dwordx4 v[38:41], v167, s[62:63]
	s_mul_i32 s0, s52, 0x300
	s_mul_i32 s1, s53, 0x300
	v_add_u32_e32 v167, s0, v195
	s_and_saveexec_b64 s[98:99], s[40:41]
	v_add_u32_e32 v167, s1, v195
	s_mov_b64 exec, s[98:99]
	global_load_dwordx2 v[36:37], v167, s[62:63] offset:16
	global_load_dwordx4 v[32:35], v167, s[62:63]
	s_mul_i32 s0, s54, 0x300
	s_mul_i32 s1, s55, 0x300
	v_add_u32_e32 v167, s0, v195
	s_and_saveexec_b64 s[98:99], s[40:41]
	v_add_u32_e32 v167, s1, v195
	s_mov_b64 exec, s[98:99]
	global_load_dwordx2 v[200:201], v167, s[62:63] offset:16
	global_load_dwordx4 v[196:199], v167, s[62:63]
	s_mul_i32 s0, s56, 0x300
	s_mul_i32 s1, s57, 0x300
	v_add_u32_e32 v167, s0, v195
	s_and_saveexec_b64 s[98:99], s[40:41]
	v_add_u32_e32 v167, s1, v195
	s_mov_b64 exec, s[98:99]
	global_load_dwordx2 v[232:233], v167, s[62:63] offset:16
; __device__ void peer_gather_phase(const Params& P, int l, bool do_store) {
;     ...
;     f32x2 xu[16];
;     {
;       const bf16_t* xq = P.XB + (size_t)t * 1024 + (lane & 31) * 32;
;       const uint4 q0 = *(const uint4*)xq, q1 = *(const uint4*)(xq + 8), q2 = *(const uint4*)(xq + 16), q3 = *(const uint4*)(xq + 24);
;       xu[0] = f32x2{lo_f(q0.x), hi_f(q0.x)}; xu[1] = f32x2{lo_f(q0.y), hi_f(q0.y)}; xu[2] = f32x2{lo_f(q0.z), hi_f(q0.z)}; xu[3] = f32x2{lo_f(q0.w), hi_f(q0.w)};
;       xu[4] = f32x2{lo_f(q1.x), hi_f(q1.x)}; xu[5] = f32x2{lo_f(q1.y), hi_f(q1.y)}; xu[6] = f32x2{lo_f(q1.z), hi_f(q1.z)}; xu[7] = f32x2{lo_f(q1.w), hi_f(q1.w)};
;       xu[8] = f32x2{lo_f(q2.x), hi_f(q2.x)}; xu[9] = f32x2{lo_f(q2.y), hi_f(q2.y)}; xu[10] = f32x2{lo_f(q2.z), hi_f(q2.z)}; xu[11] = f32x2{lo_f(q2.w), hi_f(q2.w)};
;       xu[12] = f32x2{lo_f(q3.x), hi_f(q3.x)}; xu[13] = f32x2{lo_f(q3.y), hi_f(q3.y)}; xu[14] = f32x2{lo_f(q3.z), hi_f(q3.z)}; xu[15] = f32x2{lo_f(q3.w), hi_f(q3.w)};
;     }
;     f32x2 y[8];
; #pragma unroll
;     for (int k = 0; k < 8; ++k) y[k] = f32x2{0.f, 0.f};
;     {
;       const int r4n = (r4 + (int)gridDim.x < T_TOK / 4) ? r4 + (int)gridDim.x : r4;
;       const int tn = r4n * 4 + w;
;       nev0 = P.EXP[(size_t)tn * 128 + lane]; nev1 = P.EXP[(size_t)tn * 128 + 64 + lane];
;       ngv0 = P.GATE[(size_t)tn * 128 + lane]; ngv1 = P.GATE[(size_t)tn * 128 + 64 + lane];
;       const bf16_t* xbn = P.XB + (size_t)tn * 1024 + lane * 16;
;       nxa = *(const uint4*)xbn; nxc = *(const uint4*)(xbn + 8);
;     }
;     const float sux0 = SU[ev0], sux1 = SU[ev1];
;     const float gsx0 = gv0 * SV[ev0], gsx1 = gv1 * SV[ev1];
;     const bool uphi = (lane >= 32);
;     uint2 uA[12], uB[12]; uint2 vA[8], vB[8];
;     auto load_batch = [&](uint2 (&u6)[12], uint2 (&v8)[8], int bt) {
;       const int evs = (bt < 8) ? ev0 : ev1;
;       const int kb = (bt & 7) * 8;
; #pragma unroll
;       for (int pr = 0; pr < 4; ++pr) {
;         const int ea = __builtin_amdgcn_readlane(evs, kb + 2 * pr), eb = __builtin_amdgcn_readlane(evs, kb + 2 * pr + 1);
;         const uint2* up = (const uint2*)(U + (size_t)(uphi ? eb : ea) * 768);
;         u6[3 * pr] = up[0]; u6[3 * pr + 1] = up[1]; u6[3 * pr + 2] = up[2];
;         v8[2 * pr] = *(const uint2*)(V + (size_t)ea * 512);
;         v8[2 * pr + 1] = *(const uint2*)(V + (size_t)eb * 512);
;       }
	global_load_dwordx4 v[228:231], v167, s[62:63]
	s_mul_i32 s0, s58, 0x300
	s_mul_i32 s1, s59, 0x300
	v_add_u32_e32 v167, s0, v195
	s_and_saveexec_b64 s[98:99], s[40:41]
	v_add_u32_e32 v167, s1, v195
	s_mov_b64 exec, s[98:99]
	global_load_dwordx2 v[238:239], v167, s[62:63] offset:16
	global_load_dwordx4 v[234:237], v167, s[62:63]
	s_mul_i32 s0, s60, 0x300
	s_mul_i32 s1, s61, 0x300
	v_add_u32_e32 v167, s0, v195
	s_and_saveexec_b64 s[98:99], s[40:41]
	v_add_u32_e32 v167, s1, v195
	s_mov_b64 exec, s[98:99]
	global_load_dwordx2 v[244:245], v167, s[62:63] offset:16
	global_load_dwordx4 v[240:243], v167, s[62:63]
	s_lshl_b32 s0, s46, 9
	s_add_u32 s0, s64, s0
	s_addc_u32 s1, s65, 0
	global_load_dwordx2 v[144:145], v227, s[0:1]
	s_lshl_b32 s0, s47, 9
	s_add_u32 s0, s64, s0
	s_addc_u32 s1, s65, 0
	global_load_dwordx2 v[146:147], v227, s[0:1]
	s_lshl_b32 s0, s48, 9
	s_add_u32 s0, s64, s0
	s_addc_u32 s1, s65, 0
	global_load_dwordx2 v[148:149], v227, s[0:1]
	s_lshl_b32 s0, s49, 9
	s_add_u32 s0, s64, s0
	s_addc_u32 s1, s65, 0
	global_load_dwordx2 v[150:151], v227, s[0:1]
	s_lshl_b32 s0, s50, 9
	s_add_u32 s0, s64, s0
	s_addc_u32 s1, s65, 0
	global_load_dwordx2 v[152:153], v227, s[0:1]
	s_lshl_b32 s0, s51, 9
	s_add_u32 s0, s64, s0
	s_addc_u32 s1, s65, 0
	global_load_dwordx2 v[154:155], v227, s[0:1]
	s_lshl_b32 s0, s52, 9
	s_add_u32 s0, s64, s0
	s_addc_u32 s1, s65, 0
	global_load_dwordx2 v[156:157], v227, s[0:1]
	s_lshl_b32 s0, s53, 9
	s_add_u32 s0, s64, s0
	s_addc_u32 s1, s65, 0
	global_load_dwordx2 v[158:159], v227, s[0:1]
	s_lshl_b32 s0, s54, 9
	s_add_u32 s0, s64, s0
	s_addc_u32 s1, s65, 0
	global_load_dwordx2 v[168:169], v227, s[0:1]
	s_lshl_b32 s0, s55, 9
	s_add_u32 s0, s64, s0
	s_addc_u32 s1, s65, 0
	global_load_dwordx2 v[170:171], v227, s[0:1]
	s_lshl_b32 s0, s56, 9
	s_add_u32 s0, s64, s0
	s_addc_u32 s1, s65, 0
	global_load_dwordx2 v[172:173], v227, s[0:1]
	s_lshl_b32 s0, s57, 9
	s_add_u32 s0, s64, s0
	s_addc_u32 s1, s65, 0
	global_load_dwordx2 v[174:175], v227, s[0:1]
	s_lshl_b32 s0, s58, 9
	s_add_u32 s0, s64, s0
	s_addc_u32 s1, s65, 0
	global_load_dwordx2 v[180:181], v227, s[0:1]
	s_lshl_b32 s0, s59, 9
	s_add_u32 s0, s64, s0
	s_addc_u32 s1, s65, 0
	global_load_dwordx2 v[182:183], v227, s[0:1]
	s_lshl_b32 s0, s60, 9
	s_add_u32 s0, s64, s0
	s_addc_u32 s1, s65, 0
	global_load_dwordx2 v[184:185], v227, s[0:1]
	s_lshl_b32 s0, s61, 9
	s_add_u32 s0, s64, s0
	s_addc_u32 s1, s65, 0
	global_load_dwordx2 v[186:187], v227, s[0:1]
	global_load_dword v91, v[20:21], off
	global_load_dword v93, v[20:21], off offset:256
	v_lshlrev_b64 v[94:95], 10, v[16:17]
	s_mov_b32 s6, 0
	s_mov_b32 s4, 7
	v_mov_b32_e32 v131, v130
	v_mov_b32_e32 v138, v130
	v_mov_b32_e32 v139, v130
	v_mov_b32_e32 v140, v130
	v_mov_b32_e32 v141, v130
	v_mov_b32_e32 v142, v130
	v_mov_b32_e32 v143, v130
	v_mov_b32_e32 v128, v130
	v_mov_b32_e32 v129, v130
	v_mov_b32_e32 v132, v130
	v_mov_b32_e32 v133, v130
	v_mov_b32_e32 v134, v130
	v_mov_b32_e32 v135, v130
	v_mov_b32_e32 v136, v130
	v_mov_b32_e32 v137, v130
	s_movk_i32 s42, 0x300
	s_waitcnt vmcnt(45)
	v_lshlrev_b32_e32 v120, 16, v0
	s_waitcnt vmcnt(44)
	v_lshlrev_b32_e32 v112, 16, v4
	s_waitcnt vmcnt(43)
	v_lshlrev_b32_e32 v104, 16, v8
	s_waitcnt vmcnt(42)
	v_lshlrev_b32_e32 v96, 16, v12
	v_and_b32_e32 v97, 0xffff0000, v12
	v_lshlrev_b32_e32 v98, 16, v13
	v_and_b32_e32 v99, 0xffff0000, v13
	v_lshlrev_b32_e32 v100, 16, v14
	v_and_b32_e32 v101, 0xffff0000, v14
	v_lshlrev_b32_e32 v102, 16, v15
	v_and_b32_e32 v103, 0xffff0000, v15
	v_and_b32_e32 v105, 0xffff0000, v8
	v_lshlrev_b32_e32 v106, 16, v9
	v_and_b32_e32 v107, 0xffff0000, v9
	v_lshlrev_b32_e32 v108, 16, v10
	v_and_b32_e32 v109, 0xffff0000, v10
	v_lshlrev_b32_e32 v110, 16, v11
	v_and_b32_e32 v111, 0xffff0000, v11
	v_and_b32_e32 v113, 0xffff0000, v4
	v_lshlrev_b32_e32 v114, 16, v5
	v_and_b32_e32 v115, 0xffff0000, v5
	v_lshlrev_b32_e32 v116, 16, v6
	v_and_b32_e32 v117, 0xffff0000, v6
	v_lshlrev_b32_e32 v118, 16, v7
	v_and_b32_e32 v119, 0xffff0000, v7
	v_and_b32_e32 v121, 0xffff0000, v0
	v_lshlrev_b32_e32 v122, 16, v1
	v_and_b32_e32 v123, 0xffff0000, v1
	v_lshlrev_b32_e32 v124, 16, v2
	v_and_b32_e32 v125, 0xffff0000, v2
	v_lshlrev_b32_e32 v126, 16, v3
	v_and_b32_e32 v127, 0xffff0000, v3
	s_waitcnt vmcnt(35)
	v_mul_f32_e32 v191, v29, v24
	s_waitcnt vmcnt(34)
	v_mul_f32_e32 v192, v28, v22
